# attention work queue: next unit's ticket prefetched during the current unit's tail
# speedup vs baseline: 1.0027x; 1.0027x over previous
; __global__ void __launch_bounds__(NWAVES * 64, 2) hymba_fwd(Args args) {
;     ...
;         __syncthreads();
;         const float lam = ((const float*)ctl)[CW_LAM];
;         constexpr int NU = 512 + 1024;
;         for (;;) {
;             if (tid == 0) MISC[0] = atomicAdd(ctl + CW_QCTR, 1u);
;             __syncthreads();
;             const int u = (int)MISC[0];
.LBB0_290:
	v_mov_b32_e32 v177, 0
	s_barrier
	global_load_dword v183, v177, s[70:71] offset:256
	v_mbcnt_hi_u32_b32 v211, -1, v124
	s_add_i32 s15, 0, 0x20000
	s_mov_b32 s48, 2.0
	s_mov_b32 s50, 0x41000000
	s_mov_b32 s58, 0x41200000
	s_mov_b32 s64, 0x41800000
	s_mov_b32 s80, 0x41900000
	s_mov_b32 s82, 0x41c00000
	s_mov_b32 s86, -2.0
	s_mov_b32 s88, 0xc1000000
	s_mov_b32 s90, 0xc1200000
	s_mov_b32 s92, 0xc1800000
	s_mov_b32 s94, 0xc1900000
	s_mov_b32 s96, 0xc1c00000
	s_mov_b32 s4, 0xc1d00000
	s_waitcnt vmcnt(3)
	v_and_b32_e32 v0, 64, v211
	s_mov_b32 s11, 0
	v_mov_b32_e32 v219, s15
	s_mov_b32 s26, 0xf800000
	v_mov_b32_e32 v220, 0x260
	s_movk_i32 s27, 0xd00
	s_movk_i32 s28, 0x100
	s_add_i32 s29, 0, 0x10010
	s_mov_b32 s14, 0x41d00000
	s_mov_b32 s49, 0x40400000
	s_mov_b32 s51, 0x41100000
	s_mov_b32 s59, 0x41300000
	s_mov_b32 s65, 0x41880000
	s_mov_b32 s81, 0x41980000
	s_mov_b32 s83, 0x41c80000
	s_mov_b32 s84, 0xc2000000
	s_mov_b32 s87, 0xc0400000
	s_mov_b32 s89, 0xc1100000
	s_mov_b32 s91, 0xc1300000
	s_mov_b32 s93, 0xc1880000
	s_mov_b32 s95, 0xc1980000
	s_mov_b32 s97, 0xc1c80000
	s_mov_b32 s5, 0xc1d80000
	v_mov_b32_e32 v221, 0x358637bd
	s_movk_i32 s30, 0x7fff
	v_mov_b32_e32 v223, 0x3c800000
	v_xor_b32_e32 v214, 32, v211
	v_add_u32_e32 v213, 64, v0
	v_xor_b32_e32 v252, 1, v211
	v_xor_b32_e32 v253, 2, v211
	v_xor_b32_e32 v254, 4, v211
	v_xor_b32_e32 v212, 8, v211
	v_xor_b32_e32 v218, 16, v211
	v_mov_b32_e32 v178, 0x41d00000
	s_and_saveexec_b64 s[98:99], s[22:23]
	s_cbranch_execz .Lattn_q0
	v_mov_b32_e32 v175, 1
	global_atomic_add v175, v177, v175, s[70:71] sc0
.Lattn_q0:
	s_or_b64 exec, exec, s[98:99]
	s_branch .LBB0_293

; __global__ void __launch_bounds__(NWAVES * 64, 2) hymba_fwd(Args args) {
;     ...
;         for (;;) {
;             if (tid == 0) MISC[0] = atomicAdd(ctl + CW_QCTR, 1u);
;             __syncthreads();
;             const int u = (int)MISC[0];
;             __syncthreads();
;             if (u >= NU) break;
.LBB0_293:
	s_and_saveexec_b64 s[0:1], s[22:23]
	s_cbranch_execz .LBB0_297
	s_waitcnt vmcnt(0)
	v_mov_b32_e32 v1, s15
	ds_write_b32 v1, v175

; __device__ __forceinline__ void sc_init(f32x16& p0, f32x16& p1, float dq, float nsl2, float m_ref, int side) {
;   if (side != 0) { const float sg = (float)side; const float base0 = fmaf(sg * nsl2, dq, -m_ref), base1 = base0 - sg * 32.f * nsl2;
; #pragma unroll
;     for (int r = 0; r < 16; ++r) { const float c = -sg * nsl2 * (float)((r & 3) + 8 * (r >> 2)); p0[r] = base0 + c; p1[r] = base1 + c; }
;   } else {
; #pragma unroll
;     for (int r = 0; r < 16; ++r) { const float kv = (float)((r & 3) + 8 * (r >> 2)); const float d0 = dq - kv, d1 = d0 - 32.f;
;       p0[r] = fmaf(nsl2, __builtin_fabsf(d0), -m_ref); p1[r] = fmaf(nsl2, __builtin_fabsf(d1), -m_ref); }
;   }
; }
; __global__ void __launch_bounds__(NWAVES * 64, 2) hymba_fwd(Args args) {
;     ...
;             if (tid == 0) MISC[0] = atomicAdd(ctl + CW_QCTR, 1u);
.LBB0_337:
	s_and_saveexec_b64 s[98:99], s[22:23]
	s_cbranch_execz .Lattn_q1
	v_mov_b32_e32 v175, 1
	global_atomic_add v175, v177, v175, s[70:71] sc0
.Lattn_q1:
	s_or_b64 exec, exec, s[98:99]
	s_lshl_b32 s24, s85, 7
	s_add_i32 s0, s3, -1
	v_cvt_f32_i32_e32 v96, s0
	s_cmp_gt_i32 s0, s73
	s_cselect_b64 s[0:1], -1, 0
	s_cmp_gt_i32 s3, s72
	v_fmac_f32_e32 v184, 0xc2800000, v96
	v_cndmask_b32_e64 v96, 0, -1, s[0:1]
	s_cselect_b64 vcc, -1, 0
	v_cndmask_b32_e32 v96, 1, v96, vcc
	v_cmp_ne_u32_e32 vcc, 0, v96
	s_cbranch_vccz .LBB0_347
	v_cvt_f32_i32_e32 v96, v96
	v_mul_f32_e32 v98, v180, v96
	v_mul_f32_e32 v97, 0x42000000, v96
	v_xor_b32_e32 v96, 0x80000000, v96
	v_fma_f32 v179, v98, v184, -v182
	v_pk_mul_f32 v[144:145], v[180:181], v[96:97] op_sel_hi:[0,1]
	v_mul_f32_e32 v112, 0, v144
	v_pk_mul_f32 v[114:115], v[144:145], s[14:15]
	v_pk_fma_f32 v[146:147], v[180:181], v[96:97], v[178:179] op_sel_hi:[0,1,1] neg_lo:[1,0,0] neg_hi:[1,0,0]
	v_mov_b32_e32 v113, v144
	v_pk_add_f32 v[96:97], v[112:113], v[146:147] op_sel:[0,1]
	v_pk_fma_f32 v[98:99], v[144:145], s[48:49], v[146:147] op_sel:[0,0,1] op_sel_hi:[0,1,1]
	v_pk_fma_f32 v[100:101], v[144:145], s[50:51], v[146:147] op_sel:[0,0,1] op_sel_hi:[0,1,1]
	v_pk_fma_f32 v[102:103], v[144:145], s[58:59], v[146:147] op_sel:[0,0,1] op_sel_hi:[0,1,1]
	v_pk_fma_f32 v[104:105], v[144:145], s[64:65], v[146:147] op_sel:[0,0,1] op_sel_hi:[0,1,1]
	v_pk_fma_f32 v[106:107], v[144:145], s[80:81], v[146:147] op_sel:[0,0,1] op_sel_hi:[0,1,1]
	v_pk_fma_f32 v[108:109], v[144:145], s[82:83], v[146:147] op_sel:[0,0,1] op_sel_hi:[0,1,1]
	v_pk_fma_f32 v[110:111], v[144:145], s[14:15], v[146:147] op_sel:[0,0,1] op_sel_hi:[1,1,0]
	v_mul_f32_e32 v115, 0x41d80000, v144
	v_mov_b32_e32 v146, v179
	v_pk_add_f32 v[126:127], v[146:147], v[114:115] op_sel_hi:[0,1]
	v_pk_add_f32 v[112:113], v[146:147], v[112:113] op_sel_hi:[0,1]
	v_pk_fma_f32 v[124:125], v[144:145], s[82:83], v[146:147] op_sel_hi:[0,1,0]
	v_pk_fma_f32 v[122:123], v[144:145], s[80:81], v[146:147] op_sel_hi:[0,1,0]
	v_pk_fma_f32 v[120:121], v[144:145], s[64:65], v[146:147] op_sel_hi:[0,1,0]
	v_pk_fma_f32 v[118:119], v[144:145], s[58:59], v[146:147] op_sel_hi:[0,1,0]
	v_pk_fma_f32 v[116:117], v[144:145], s[50:51], v[146:147] op_sel_hi:[0,1,0]
	v_pk_fma_f32 v[114:115], v[144:145], s[48:49], v[146:147] op_sel_hi:[0,1,0]
	v_fmac_f32_e32 v147, 0x41d80000, v144
	v_mov_b32_e32 v111, v147
	s_cbranch_execnz .LBB0_340
